# out-projection GEMM residual epilogue (P5) de-serialized: 32 load->wait->add->store round trips per unit replaced by 4 batches of 8 residual loads in flight (loads into the free fragment registers, SG
# speedup vs baseline: 1.0192x; 1.0061x over previous
;     __device__ __forceinline__ void operator()(const f32x4 (&acc)[2][2][4][2], const Unit& u, int wr, int wc, int fr, int fq) const {
;         const int row0 = u.pm * BM + wr * 64 + fr; const int col0 = u.pn * BM + wc * 32 + 4 * fq;
;         const float* base = (u.pm * BM < split_row) ? base0 : base1;
; #pragma unroll
;         for (int ai = 0; ai < 2; ++ai)
; #pragma unroll
;             for (int m = 0; m < 4; ++m) { const size_t off = (size_t)(row0 + ai * HALF + m * 16) * ldc + col0;
; #pragma unroll
;                 for (int bj = 0; bj < 2; ++bj)
; #pragma unroll
;                     for (int n = 0; n < 2; ++n) { const f32x4 bs = *(const f32x4*)(base + off + bj * HALF + n * 16); *(f32x4*)(out + off + bj * HALF + n * 16) = bs + acc[ai][bj][m][n]; }
;                 if (m & 1) asm volatile("" ::: "memory"); }
.LBB0_562:
	v_lshl_add_u32 v152, s34, 8, v142
	v_lshl_or_b32 v154, s35, 8, v144
	v_ashrrev_i32_e32 v153, 31, v152
	v_ashrrev_i32_e32 v155, 31, v154
	v_lshlrev_b64 v[140:141], 11, v[152:153]
	s_cmp_lt_i32 s34, 32
	v_lshl_add_u64 v[140:141], v[140:141], 0, v[154:155]
	s_cselect_b32 s35, s13, s74
	s_cselect_b32 s34, s12, s73
	v_lshlrev_b64 v[140:141], 2, v[140:141]
	s_andn2_b64 vcc, exec, s[4:5]
	s_mov_b64 s[4:5], -1
	v_add_u32_e32 v212, 0x20000, v140
	v_add_u32_e32 v213, 0x40000, v140
	v_add_u32_e32 v214, 0x60000, v140
	v_add_u32_e32 v215, 0x100000, v140
	v_add_u32_e32 v216, 0x120000, v140
	v_add_u32_e32 v217, 0x140000, v140
	v_add_u32_e32 v218, 0x160000, v140
	global_load_dwordx4 v[148:151], v140, s[34:35]
	global_load_dwordx4 v[152:155], v140, s[34:35] offset:64
	global_load_dwordx4 v[156:159], v140, s[34:35] offset:512
	global_load_dwordx4 v[160:163], v140, s[34:35] offset:576
	global_load_dwordx4 v[164:167], v212, s[34:35]
	global_load_dwordx4 v[168:171], v212, s[34:35] offset:64
	global_load_dwordx4 v[172:175], v212, s[34:35] offset:512
	global_load_dwordx4 v[176:179], v212, s[34:35] offset:576
	global_load_dwordx4 v[180:183], v213, s[34:35]
	global_load_dwordx4 v[184:187], v213, s[34:35] offset:64
	global_load_dwordx4 v[188:191], v213, s[34:35] offset:512
	global_load_dwordx4 v[192:195], v213, s[34:35] offset:576
	global_load_dwordx4 v[196:199], v214, s[34:35]
	global_load_dwordx4 v[200:203], v214, s[34:35] offset:64
	global_load_dwordx4 v[204:207], v214, s[34:35] offset:512
	global_load_dwordx4 v[208:211], v214, s[34:35] offset:576
	s_waitcnt vmcnt(8)
	v_pk_add_f32 v[124:125], v[124:125], v[148:149]
	v_pk_add_f32 v[126:127], v[126:127], v[150:151]
	global_store_dwordx4 v140, v[124:127], s[48:49]
	v_pk_add_f32 v[120:121], v[120:121], v[152:153]
	v_pk_add_f32 v[122:123], v[122:123], v[154:155]
	global_store_dwordx4 v140, v[120:123], s[48:49] offset:64
	v_pk_add_f32 v[116:117], v[116:117], v[156:157]
	v_pk_add_f32 v[118:119], v[118:119], v[158:159]
	global_store_dwordx4 v140, v[116:119], s[48:49] offset:512
	v_pk_add_f32 v[104:105], v[104:105], v[160:161]
	v_pk_add_f32 v[106:107], v[106:107], v[162:163]
	global_store_dwordx4 v140, v[104:107], s[48:49] offset:576
	v_pk_add_f32 v[112:113], v[112:113], v[164:165]
	v_pk_add_f32 v[114:115], v[114:115], v[166:167]
	global_store_dwordx4 v212, v[112:115], s[48:49]
	v_pk_add_f32 v[108:109], v[108:109], v[168:169]
	v_pk_add_f32 v[110:111], v[110:111], v[170:171]
	global_store_dwordx4 v212, v[108:111], s[48:49] offset:64
	v_pk_add_f32 v[100:101], v[100:101], v[172:173]
	v_pk_add_f32 v[102:103], v[102:103], v[174:175]
	global_store_dwordx4 v212, v[100:103], s[48:49] offset:512
	v_pk_add_f32 v[88:89], v[88:89], v[176:177]
	v_pk_add_f32 v[90:91], v[90:91], v[178:179]
	global_store_dwordx4 v212, v[88:91], s[48:49] offset:576
	global_load_dwordx4 v[148:151], v215, s[34:35]
	global_load_dwordx4 v[152:155], v215, s[34:35] offset:64
	global_load_dwordx4 v[156:159], v215, s[34:35] offset:512
	global_load_dwordx4 v[160:163], v215, s[34:35] offset:576
	global_load_dwordx4 v[164:167], v216, s[34:35]
	global_load_dwordx4 v[168:171], v216, s[34:35] offset:64
	global_load_dwordx4 v[172:175], v216, s[34:35] offset:512
	global_load_dwordx4 v[176:179], v216, s[34:35] offset:576
	s_waitcnt vmcnt(8)
;     __device__ __forceinline__ void operator()(const f32x4 (&acc)[2][2][4][2], const Unit& u, int wr, int wc, int fr, int fq) const {
;         const int row0 = u.pm * BM + wr * 64 + fr; const int col0 = u.pn * BM + wc * 32 + 4 * fq;
;         const float* base = (u.pm * BM < split_row) ? base0 : base1;
; #pragma unroll
;         for (int ai = 0; ai < 2; ++ai)
; #pragma unroll
;             for (int m = 0; m < 4; ++m) { const size_t off = (size_t)(row0 + ai * HALF + m * 16) * ldc + col0;
; #pragma unroll
;                 for (int bj = 0; bj < 2; ++bj)
; #pragma unroll
;                     for (int n = 0; n < 2; ++n) { const f32x4 bs = *(const f32x4*)(base + off + bj * HALF + n * 16); *(f32x4*)(out + off + bj * HALF + n * 16) = bs + acc[ai][bj][m][n]; }
;                 if (m & 1) asm volatile("" ::: "memory"); }
	v_pk_add_f32 v[96:97], v[96:97], v[180:181]
	v_pk_add_f32 v[98:99], v[98:99], v[182:183]
	global_store_dwordx4 v213, v[96:99], s[48:49]
	v_pk_add_f32 v[92:93], v[92:93], v[184:185]
	v_pk_add_f32 v[94:95], v[94:95], v[186:187]
	global_store_dwordx4 v213, v[92:95], s[48:49] offset:64
	v_pk_add_f32 v[84:85], v[84:85], v[188:189]
	v_pk_add_f32 v[86:87], v[86:87], v[190:191]
	global_store_dwordx4 v213, v[84:87], s[48:49] offset:512
	v_pk_add_f32 v[72:73], v[72:73], v[192:193]
	v_pk_add_f32 v[74:75], v[74:75], v[194:195]
	global_store_dwordx4 v213, v[72:75], s[48:49] offset:576
	v_pk_add_f32 v[80:81], v[80:81], v[196:197]
	v_pk_add_f32 v[82:83], v[82:83], v[198:199]
	global_store_dwordx4 v214, v[80:83], s[48:49]
	v_pk_add_f32 v[76:77], v[76:77], v[200:201]
	v_pk_add_f32 v[78:79], v[78:79], v[202:203]
	global_store_dwordx4 v214, v[76:79], s[48:49] offset:64
	v_pk_add_f32 v[68:69], v[68:69], v[204:205]
	v_pk_add_f32 v[70:71], v[70:71], v[206:207]
	global_store_dwordx4 v214, v[68:71], s[48:49] offset:512
	v_pk_add_f32 v[64:65], v[64:65], v[208:209]
	v_pk_add_f32 v[66:67], v[66:67], v[210:211]
	global_store_dwordx4 v214, v[64:67], s[48:49] offset:576
	global_load_dwordx4 v[180:183], v217, s[34:35]
	global_load_dwordx4 v[184:187], v217, s[34:35] offset:64
	global_load_dwordx4 v[188:191], v217, s[34:35] offset:512
	global_load_dwordx4 v[192:195], v217, s[34:35] offset:576
	global_load_dwordx4 v[196:199], v218, s[34:35]
	global_load_dwordx4 v[200:203], v218, s[34:35] offset:64
	global_load_dwordx4 v[204:207], v218, s[34:35] offset:512
	global_load_dwordx4 v[208:211], v218, s[34:35] offset:576
	s_waitcnt vmcnt(8)
	v_pk_add_f32 v[60:61], v[60:61], v[148:149]
	v_pk_add_f32 v[62:63], v[62:63], v[150:151]
	global_store_dwordx4 v215, v[60:63], s[48:49]
	v_pk_add_f32 v[56:57], v[56:57], v[152:153]
	v_pk_add_f32 v[58:59], v[58:59], v[154:155]
	global_store_dwordx4 v215, v[56:59], s[48:49] offset:64
	v_pk_add_f32 v[52:53], v[52:53], v[156:157]
	v_pk_add_f32 v[54:55], v[54:55], v[158:159]
	global_store_dwordx4 v215, v[52:55], s[48:49] offset:512
	v_pk_add_f32 v[40:41], v[40:41], v[160:161]
	v_pk_add_f32 v[42:43], v[42:43], v[162:163]
	global_store_dwordx4 v215, v[40:43], s[48:49] offset:576
	v_pk_add_f32 v[48:49], v[48:49], v[164:165]
	v_pk_add_f32 v[50:51], v[50:51], v[166:167]
	global_store_dwordx4 v216, v[48:51], s[48:49]
	v_pk_add_f32 v[44:45], v[44:45], v[168:169]
	v_pk_add_f32 v[46:47], v[46:47], v[170:171]
	global_store_dwordx4 v216, v[44:47], s[48:49] offset:64
	v_pk_add_f32 v[36:37], v[36:37], v[172:173]
	v_pk_add_f32 v[38:39], v[38:39], v[174:175]
	global_store_dwordx4 v216, v[36:39], s[48:49] offset:512
	v_pk_add_f32 v[24:25], v[24:25], v[176:177]
	v_pk_add_f32 v[26:27], v[26:27], v[178:179]
	global_store_dwordx4 v216, v[24:27], s[48:49] offset:576
	s_waitcnt vmcnt(0)
	v_pk_add_f32 v[32:33], v[32:33], v[180:181]
	v_pk_add_f32 v[34:35], v[34:35], v[182:183]
	global_store_dwordx4 v217, v[32:35], s[48:49]
	v_pk_add_f32 v[28:29], v[28:29], v[184:185]
	v_pk_add_f32 v[30:31], v[30:31], v[186:187]
	global_store_dwordx4 v217, v[28:31], s[48:49] offset:64
	v_pk_add_f32 v[20:21], v[20:21], v[188:189]
	v_pk_add_f32 v[22:23], v[22:23], v[190:191]
	global_store_dwordx4 v217, v[20:23], s[48:49] offset:512
	v_pk_add_f32 v[8:9], v[8:9], v[192:193]
	v_pk_add_f32 v[10:11], v[10:11], v[194:195]
	global_store_dwordx4 v217, v[8:11], s[48:49] offset:576
	v_pk_add_f32 v[16:17], v[16:17], v[196:197]
	v_pk_add_f32 v[18:19], v[18:19], v[198:199]
	global_store_dwordx4 v218, v[16:19], s[48:49]
	v_pk_add_f32 v[12:13], v[12:13], v[200:201]
	v_pk_add_f32 v[14:15], v[14:15], v[202:203]
	global_store_dwordx4 v218, v[12:15], s[48:49] offset:64
	v_pk_add_f32 v[4:5], v[4:5], v[204:205]
	v_pk_add_f32 v[6:7], v[6:7], v[206:207]
	global_store_dwordx4 v218, v[4:7], s[48:49] offset:512
	v_pk_add_f32 v[0:1], v[0:1], v[208:209]
	v_pk_add_f32 v[2:3], v[2:3], v[210:211]
	global_store_dwordx4 v218, v[0:3], s[48:49] offset:576
	s_cbranch_vccnz .LBB0_555
	s_andn2_b64 vcc, exec, s[6:7]
	s_cbranch_vccnz .LBB0_554
	s_barrier
	s_branch .LBB0_554
